# attention item loop as well: static s_setprio 1 for waves 4-7, reset at the loop exit
# speedup vs baseline: 1.0013x; 1.0013x over previous
.LBB0_1129:
	v_add_co_u32_e32 v20, vcc, s21, v16
	s_not_b32 s63, s14
	s_nop 0
	v_addc_co_u32_e32 v21, vcc, 0, v17, vcc
	v_add_co_u32_e32 v24, vcc, s22, v16
	v_readlane_b32 s10, v254, 49
	s_nop 0
	v_addc_co_u32_e32 v25, vcc, 0, v17, vcc
	v_add_co_u32_e32 v28, vcc, s23, v16
	global_load_dwordx4 v[20:23], v[20:21], off
	s_nop 0
	global_load_dwordx4 v[24:27], v[24:25], off
	v_addc_co_u32_e32 v29, vcc, 0, v17, vcc
	v_add_co_u32_e32 v32, vcc, s24, v16
	s_movk_i32 s14, 0xf0
	s_nop 0
	v_addc_co_u32_e32 v33, vcc, 0, v17, vcc
	v_add_co_u32_e32 v36, vcc, s15, v16
	global_load_dwordx4 v[28:31], v[28:29], off
	s_nop 0
	global_load_dwordx4 v[32:35], v[32:33], off
	v_addc_co_u32_e32 v37, vcc, 0, v17, vcc
	v_add_co_u32_e32 v40, vcc, s18, v16
	v_readlane_b32 s11, v254, 50
	s_nop 0
	v_addc_co_u32_e32 v41, vcc, 0, v17, vcc
	v_add_co_u32_e32 v44, vcc, s19, v16
	global_load_dwordx4 v[36:39], v[36:37], off
	s_nop 0
	global_load_dwordx4 v[40:43], v[40:41], off
	v_addc_co_u32_e32 v45, vcc, 0, v17, vcc
	v_add_co_u32_e32 v16, vcc, s20, v16
	s_and_b64 s[10:11], s[10:11], exec
	s_nop 0
	v_addc_co_u32_e32 v17, vcc, 0, v17, vcc
	global_load_dwordx4 v[44:47], v[44:45], off
	s_nop 0
	global_load_dwordx4 v[48:51], v[16:17], off
	v_xor_b32_e32 v16, v128, v19
	v_lshlrev_b32_e32 v17, 8, v128
	v_lshlrev_b32_e32 v54, 4, v16
	v_and_or_b32 v17, v54, s14, v17
	s_load_dwordx2 s[14:15], s[8:9], 0x70
	s_cselect_b32 s10, 0, 8
	s_lshl_b32 s11, 1, s40
	s_add_u32 s20, s4, s13
	s_addc_u32 s21, s5, 0
	s_waitcnt lgkmcnt(0)
	s_add_u32 s22, s14, 0x1100000
	v_cvt_f32_u32_e32 v152, s11
	s_addc_u32 s23, s15, 0
	s_lshl_b32 s11, s12, 4
	v_and_b32_e32 v149, 63, v19
	s_or_b32 s11, s11, 1
	s_cmp_gt_i32 s28, 0
	v_cmp_gt_u32_e64 s[42:43], 32, v149
	s_cselect_b64 s[24:25], -1, 0
	s_add_i32 s18, s40, 13
	s_and_b64 s[26:27], s[0:1], s[42:43]
	s_cmp_gt_i32 s28, 1
	s_cselect_b64 s[28:29], -1, 0
	s_add_i32 s0, s40, 12
	s_lshl_b64 s[60:61], 1, s0
	v_writelane_b32 v254, s60, 52
	v_bfe_u32 v53, v19, 5, 1
	v_and_b32_e32 v150, 31, v19
	v_writelane_b32 v254, s61, 53
	s_lshl_b64 s[60:61], 2, s0
	v_writelane_b32 v254, s60, 54
	v_ashrrev_i32_e32 v130, 2, v19
	v_lshlrev_b32_e32 v19, 4, v19
	v_lshlrev_b32_e32 v138, 4, v53
	v_writelane_b32 v254, s61, 55
	s_lshl_b64 s[60:61], 3, s0
	v_and_b32_e32 v16, 48, v19
	v_add_u32_e32 v151, 0, v17
	v_lshl_add_u64 v[132:133], s[6:7], 0, v[138:139]
	v_readlane_b32 s6, v253, 56
	v_mov_b32_e32 v17, v139
	v_writelane_b32 v254, s60, 56
	s_waitcnt vmcnt(8)
	ds_write_b128 v151, v[0:3]
	ds_write_b128 v151, v[8:11] offset:8192
	ds_write_b128 v151, v[4:7] offset:16384
	ds_write_b128 v151, v[12:15] offset:24576
	v_or_b32_e32 v2, s6, v150
	v_lshl_add_u64 v[0:1], s[14:15], 0, v[16:17]
	s_mov_b64 s[6:7], 0xc000000
	v_readlane_b32 s1, v253, 51
	v_writelane_b32 v254, s61, 57
	s_lshl_b64 s[60:61], 4, s0
	v_lshl_add_u64 v[134:135], v[0:1], 0, s[6:7]
	v_mov_b32_e32 v0, s1
	s_movk_i32 s1, 0x210
	v_writelane_b32 v254, s60, 58
	v_lshlrev_b32_e32 v52, 3, v18
	v_mad_u32_u24 v4, v150, s1, v0
	v_readlane_b32 s1, v253, 47
	v_writelane_b32 v254, s61, 59
	s_lshl_b64 s[60:61], 5, s0
	s_movk_i32 s50, 0x310
	v_lshl_add_u32 v160, v150, 2, s1
	v_lshlrev_b32_e32 v0, 1, v52
	v_mov_b32_e32 v1, v139
	v_readlane_b32 s1, v253, 53
	v_writelane_b32 v254, s60, 60
	v_mul_lo_u32 v55, v130, s50
	v_lshl_add_u64 v[136:137], s[4:5], 0, v[0:1]
	v_lshl_add_u32 v0, v2, 8, 0
	v_xor_b32_e32 v1, v53, v18
	v_bitop3_b32 v2, v53, v18, 2 bitop3:0x36
	v_bitop3_b32 v5, v53, v18, 4 bitop3:0x36
	v_bitop3_b32 v6, v53, v18, 6 bitop3:0x36
	v_bitop3_b32 v7, v53, v18, 8 bitop3:0x36
	v_bitop3_b32 v8, v53, v18, 10 bitop3:0x36
	v_bitop3_b32 v9, v53, v18, 12 bitop3:0x36
	v_bitop3_b32 v10, v53, v18, 14 bitop3:0x36
	v_add_u32_e32 v12, s1, v138
	v_writelane_b32 v254, s61, 61
	s_lshl_b64 s[60:61], 6, s0
	s_lshl_b64 s[0:1], 7, s0
	v_or_b32_e32 v19, 0x80, v150
	v_lshlrev_b32_e32 v157, 2, v53
	v_add_u32_e32 v3, 0, v55
	v_lshlrev_b32_e32 v1, 4, v1
	v_lshlrev_b32_e32 v2, 4, v2
	v_lshlrev_b32_e32 v5, 4, v5
	v_lshlrev_b32_e32 v6, 4, v6
	v_lshlrev_b32_e32 v7, 4, v7
	v_lshlrev_b32_e32 v8, 4, v8
	v_lshlrev_b32_e32 v9, 4, v9
	v_lshlrev_b32_e32 v10, 4, v10
	s_lshl_b64 s[4:5], 32, s53
	s_lshl_b64 s[12:13], 64, s53
	s_lshl_b64 s[14:15], 0x60, s53
	s_lshl_b64 s[44:45], 0x80, s53
	s_lshl_b64 s[46:47], 0xa0, s53
	s_lshl_b64 s[48:49], 0xc0, s53
	s_lshl_b64 s[72:73], 0xe0, s53
	s_lshl_b64 s[74:75], 0x100, s53
	s_lshl_b64 s[76:77], 0x120, s53
	s_lshl_b64 s[78:79], 0x140, s53
	s_lshl_b64 s[80:81], 0x160, s53
	v_mul_u32_u24_e32 v11, 0x310, v150
	v_mad_u32_u24 v13, v150, s50, v174
	v_writelane_b32 v254, s60, 62
	v_writelane_b32 v255, s0, 0
	s_mov_b32 s51, 0x16000
	v_add_u32_e32 v153, 0x10000, v151
	v_add_u32_e32 v154, 0x12000, v151
	v_add_u32_e32 v155, 0x14000, v151
	v_add_u32_e32 v156, 0x16000, v151
	v_sub_u32_e32 v158, v19, v157
	v_cvt_f32_ubyte0_e32 v159, v157
	v_ashrrev_i32_e32 v131, 31, v130
	s_lshl_b64 s[30:31], 1, s18
	s_lshl_b64 s[54:55], 2, s18
	s_lshl_b64 s[34:35], 3, s18
	s_lshl_b64 s[36:37], 4, s18
	s_lshl_b64 s[38:39], 5, s18
	s_lshl_b64 s[6:7], 6, s18
	s_lshl_b64 s[18:19], 7, s18
	v_writelane_b32 v254, s61, 63
	v_writelane_b32 v255, s1, 1
	s_lshl_b64 s[0:1], 0x2000, s40
	s_lshl_b32 s60, s4, 1
	s_lshl_b32 s64, s12, 1
	s_lshl_b32 s66, s14, 1
	s_lshl_b32 s56, s44, 1
	s_lshl_b32 s68, s46, 1
	s_lshl_b32 s70, s48, 1
	s_lshl_b32 s72, s72, 1
	s_lshl_b32 s74, s74, 1
	s_lshl_b32 s76, s76, 1
	s_lshl_b32 s78, s78, 1
	s_lshl_b32 s80, s80, 1
	v_add_u32_e32 v161, v3, v16
	v_add_u32_e32 v162, v4, v138
	v_add_u32_e32 v163, v0, v1
	v_add_u32_e32 v164, v0, v2
	v_add_u32_e32 v165, v0, v5
	v_add_u32_e32 v166, v0, v6
	v_add_u32_e32 v167, v0, v7
	v_add_u32_e32 v168, v0, v8
	v_add_u32_e32 v169, v0, v9
	v_add_u32_e32 v170, v0, v10
	v_add_u32_e32 v171, v12, v11
	v_add_u32_e32 v191, v12, v13
	s_lshl_b64 s[82:83], 0x4000, s40
	s_lshl_b64 s[84:85], 0x6000, s40
	s_lshl_b64 s[86:87], 0x8000, s40
	s_lshl_b64 s[88:89], 0xa000, s40
	s_lshl_b64 s[90:91], 0xc000, s40
	s_lshl_b64 s[92:93], 0xe000, s40
	s_waitcnt vmcnt(7)
	ds_write_b128 v151, v[20:23] offset:32768
	s_waitcnt vmcnt(6)
	ds_write_b128 v151, v[24:27] offset:40960
	s_waitcnt vmcnt(5)
	ds_write_b128 v151, v[28:31] offset:49152
	s_waitcnt vmcnt(4)
	ds_write_b128 v151, v[32:35] offset:57344
	s_waitcnt vmcnt(3)
	ds_write_b128 v153, v[36:39]
	s_waitcnt vmcnt(2)
	ds_write_b128 v154, v[40:43]
	s_waitcnt vmcnt(1)
	ds_write_b128 v155, v[44:47]
	s_waitcnt vmcnt(0)
	ds_write_b128 v156, v[48:51]
	v_mov_b32_e32 v178, v36
	v_mov_b32_e32 v179, v37
	v_mov_b32_e32 v180, v38
	v_mov_b32_e32 v181, v39
	v_mov_b32_e32 v182, v40
	v_mov_b32_e32 v183, v41
	v_mov_b32_e32 v184, v42
	v_mov_b32_e32 v185, v43
	v_mov_b32_e32 v186, v44
	v_mov_b32_e32 v187, v45
	v_mov_b32_e32 v188, v46
	v_mov_b32_e32 v189, v47
	v_mov_b32_e32 v190, v48
	v_mov_b32_e32 v172, v49
	v_mov_b32_e32 v173, v50
	v_mov_b32_e32 v174, v51
	v_readlane_b32 s98, v253, 56
	s_nop 1
	s_cmp_lt_u32 s98, 0x80
	s_cbranch_scc1 .Lattprio_skip
	s_setprio 1
.Lattprio_skip:
	s_branch .LBB0_1131
.LBB0_1130:
	s_andn2_b64 vcc, exec, s[12:13]
	s_mov_b32 s94, s50
	s_cbranch_vccz .LBB0_1245

.LBB0_1245:
	s_setprio 0
	v_mov_b32_e32 v172, 0x358637bd
	v_mov_b32_e32 v173, 1
	v_mov_b32_e32 v174, 0x12600
	v_mov_b32_e32 v178, 0x630
	v_mov_b32_e32 v179, 0x840
	v_mov_b32_e32 v180, 0xa50
	v_mov_b32_e32 v181, 0xc60
	v_mov_b32_e32 v182, 0xe70
	v_mov_b32_e32 v183, 0x1080
	v_mov_b32_e32 v184, 0x1290
	v_mov_b32_e32 v185, 0x14a0
	v_mov_b32_e32 v186, 0x16b0
	v_mov_b32_e32 v187, 0x18c0
	v_readlane_b32 s0, v253, 49
	v_readlane_b32 s4, v254, 49
	v_readlane_b32 s1, v253, 50
	v_readlane_b32 s5, v254, 50
	s_or_b64 s[0:1], s[4:5], s[0:1]
	s_waitcnt vmcnt(0)
	v_and_b32_e32 v4, 63, v148
	s_and_b64 vcc, exec, s[0:1]
	v_readlane_b32 s39, v254, 0
	s_mov_b32 s53, 0x20000
	s_mov_b32 s63, 0x10000
	v_readlane_b32 s26, v254, 51
	s_waitcnt lgkmcnt(0)
	s_barrier
	s_cbranch_vccnz .LBB0_1248
	s_load_dwordx2 s[0:1], s[8:9], 0x70
	v_lshlrev_b32_e32 v0, 3, v4
	v_and_b32_e32 v0, 56, v0
	v_lshrrev_b32_e32 v5, 5, v4
	v_and_b32_e32 v2, 31, v148
	v_readlane_b32 s4, v253, 52
	v_lshrrev_b32_e32 v6, 3, v4
	v_lshlrev_b32_e32 v138, 1, v0
	v_lshl_add_u32 v3, v2, 2, s4
	v_mul_u32_u24_e32 v11, 0x84, v5
	v_mul_u32_u24_e32 v7, 0x84, v0
	s_waitcnt lgkmcnt(0)
	v_lshl_add_u64 v[0:1], s[0:1], 0, v[138:139]
	s_mov_b64 s[0:1], 0x1200000
	v_lshlrev_b32_e32 v8, 2, v6
	v_lshl_add_u64 v[0:1], v[0:1], 0, s[0:1]
	v_add3_u32 v7, s4, v7, v8
	v_or_b32_e32 v8, 8, v6
	v_or_b32_e32 v9, 16, v6
	v_or_b32_e32 v10, 24, v6
	v_lshlrev_b32_e32 v138, 2, v2
	v_add_u32_e32 v11, v3, v11
	v_readlane_b32 s4, v253, 57
	v_readlane_b32 s5, v253, 54
	v_readlane_b32 s6, v253, 48
	v_readlane_b32 s12, v253, 55
	v_readlane_b32 s13, v253, 58
	s_mov_b32 s14, 0x12000
	s_mov_b32 s15, 0x14000
	s_mov_b32 s18, 0x16000
	s_mov_b32 s19, 0x8000
	s_mov_b32 s20, 0xa000
	s_mov_b32 s21, 0xc000
	s_mov_b32 s22, 0xe000
	s_mov_b32 s23, 0x30000
